# in-proj tile scheduler resumes its patch scan after the current unit instead of rescanning from it=0 before every unit (O(1) SALU per unit)
# speedup vs baseline: 1.0150x; 1.0108x over previous
.LBB0_623:
	s_mov_b64 s[42:43], s[48:49]
	s_mov_b64 s[44:45], s[50:51]
	v_mov_b32_e32 v144, v137
	s_mov_b32 s60, s6
	s_mov_b32 s61, s7
	s_mov_b32 s0, s35
	s_add_i32 s35, s35, 1
	s_mov_b32 s63, -1
	s_mov_b32 s1, 0
	s_mov_b32 s22, 0
	s_mov_b32 s30, 0
	s_cmp_eq_u32 s0, 0
	s_cbranch_scc1 .Lsr_ip1
	s_mov_b32 s63, s0
	s_mov_b32 s30, s100
	s_mov_b32 s22, s100
	s_lshr_b32 s1, s100, 3
	s_mul_i32 s1, s1, s94
.Lsr_ip1:
.LBB0_624:
	s_mov_b32 s68, s90
	s_and_b64 vcc, exec, s[40:41]
	s_mov_b64 s[66:67], -1
	s_cbranch_vccnz .LBB0_627
	s_add_i32 s39, s68, s1
	s_mov_b64 s[66:67], 0
	s_cmpk_gt_i32 s39, 0x131f
	s_mov_b64 s[20:21], 0
	s_mov_b32 s64, s65
	s_mov_b32 s62, s37
	s_cbranch_scc1 .LBB0_627
	s_mul_hi_i32 s20, s39, 0x78787879
	s_lshr_b32 s21, s20, 31
	s_ashr_i32 s20, s20, 4
	s_add_i32 s62, s20, s21
	s_mul_i32 s20, s62, 0xffffffde
	s_add_i32 s64, s39, s20
	s_mov_b64 s[20:21], -1

.LBB0_644:
	s_mov_b32 s100, s30
	s_and_b64 s[0:1], s[58:59], exec
	s_cselect_b32 s0, s49, s43
	s_cselect_b32 s1, s48, s42
	s_cselect_b32 s20, s51, s45
	s_cselect_b32 s21, s50, s44
	s_add_u32 s42, s42, 0x40080
	s_addc_u32 s43, s43, 0
	s_add_u32 s22, s44, 0x100
	v_mov_b32_e32 v0, 0
	s_addc_u32 s30, s45, 0
	s_mov_b32 s64, -2
	v_mov_b32_e32 v1, v0
	v_mov_b32_e32 v2, v0
	v_mov_b32_e32 v3, v0
	v_mov_b32_e32 v4, v0
	v_mov_b32_e32 v5, v0
	v_mov_b32_e32 v6, v0
	v_mov_b32_e32 v7, v0
	v_mov_b32_e32 v8, v0
	v_mov_b32_e32 v9, v0
	v_mov_b32_e32 v10, v0
	v_mov_b32_e32 v11, v0
	v_mov_b32_e32 v12, v0
	v_mov_b32_e32 v13, v0
	v_mov_b32_e32 v14, v0
	v_mov_b32_e32 v15, v0
	v_mov_b32_e32 v24, v0
	v_mov_b32_e32 v25, v0
	v_mov_b32_e32 v26, v0
	v_mov_b32_e32 v27, v0
	v_mov_b32_e32 v28, v0
	v_mov_b32_e32 v29, v0
	v_mov_b32_e32 v30, v0
	v_mov_b32_e32 v31, v0
	v_mov_b32_e32 v40, v0
	v_mov_b32_e32 v41, v0
	v_mov_b32_e32 v42, v0
	v_mov_b32_e32 v43, v0
	v_mov_b32_e32 v44, v0
	v_mov_b32_e32 v45, v0
	v_mov_b32_e32 v46, v0
	v_mov_b32_e32 v47, v0
	v_mov_b32_e32 v16, v0
	v_mov_b32_e32 v17, v0
	v_mov_b32_e32 v18, v0
	v_mov_b32_e32 v19, v0
	v_mov_b32_e32 v20, v0
	v_mov_b32_e32 v21, v0
	v_mov_b32_e32 v22, v0
	v_mov_b32_e32 v23, v0
	v_mov_b32_e32 v32, v0
	v_mov_b32_e32 v33, v0
	v_mov_b32_e32 v34, v0
	v_mov_b32_e32 v35, v0
	v_mov_b32_e32 v36, v0
	v_mov_b32_e32 v37, v0
	v_mov_b32_e32 v38, v0
	v_mov_b32_e32 v39, v0
	v_mov_b32_e32 v48, v0
	v_mov_b32_e32 v49, v0
	v_mov_b32_e32 v50, v0
	v_mov_b32_e32 v51, v0
	v_mov_b32_e32 v52, v0
	v_mov_b32_e32 v53, v0
	v_mov_b32_e32 v54, v0
	v_mov_b32_e32 v55, v0
	v_mov_b32_e32 v56, v0
	v_mov_b32_e32 v57, v0
	v_mov_b32_e32 v58, v0
	v_mov_b32_e32 v59, v0
	v_mov_b32_e32 v60, v0
	v_mov_b32_e32 v61, v0
	v_mov_b32_e32 v62, v0
	v_mov_b32_e32 v63, v0
	v_mov_b32_e32 v64, v0
	v_mov_b32_e32 v65, v0
	v_mov_b32_e32 v66, v0
	v_mov_b32_e32 v67, v0
	v_mov_b32_e32 v68, v0
	v_mov_b32_e32 v69, v0
	v_mov_b32_e32 v70, v0
	v_mov_b32_e32 v71, v0
	v_mov_b32_e32 v72, v0
	v_mov_b32_e32 v73, v0
	v_mov_b32_e32 v74, v0
	v_mov_b32_e32 v75, v0
	v_mov_b32_e32 v76, v0
	v_mov_b32_e32 v77, v0
	v_mov_b32_e32 v78, v0
	v_mov_b32_e32 v79, v0
	v_mov_b32_e32 v88, v0
	v_mov_b32_e32 v89, v0
	v_mov_b32_e32 v90, v0
	v_mov_b32_e32 v91, v0
	v_mov_b32_e32 v92, v0
	v_mov_b32_e32 v93, v0
	v_mov_b32_e32 v94, v0
	v_mov_b32_e32 v95, v0
	v_mov_b32_e32 v104, v0
	v_mov_b32_e32 v105, v0
	v_mov_b32_e32 v106, v0
	v_mov_b32_e32 v107, v0
	v_mov_b32_e32 v108, v0
	v_mov_b32_e32 v109, v0
	v_mov_b32_e32 v110, v0
	v_mov_b32_e32 v111, v0
	v_mov_b32_e32 v80, v0
	v_mov_b32_e32 v81, v0
	v_mov_b32_e32 v82, v0
	v_mov_b32_e32 v83, v0
	v_mov_b32_e32 v84, v0
	v_mov_b32_e32 v85, v0
	v_mov_b32_e32 v86, v0
	v_mov_b32_e32 v87, v0
	v_mov_b32_e32 v96, v0
	v_mov_b32_e32 v97, v0
	v_mov_b32_e32 v98, v0
	v_mov_b32_e32 v99, v0
	v_mov_b32_e32 v100, v0
	v_mov_b32_e32 v101, v0
	v_mov_b32_e32 v102, v0
	v_mov_b32_e32 v103, v0
	v_mov_b32_e32 v112, v0
	v_mov_b32_e32 v113, v0
	v_mov_b32_e32 v114, v0
	v_mov_b32_e32 v115, v0
	v_mov_b32_e32 v116, v0
	v_mov_b32_e32 v117, v0
	v_mov_b32_e32 v118, v0
	v_mov_b32_e32 v119, v0
	v_mov_b32_e32 v120, v0
	v_mov_b32_e32 v121, v0
	v_mov_b32_e32 v122, v0
	v_mov_b32_e32 v123, v0
	v_mov_b32_e32 v124, v0
	v_mov_b32_e32 v125, v0
	v_mov_b32_e32 v126, v0
	v_mov_b32_e32 v127, v0

.LBB0_1158:
	s_mov_b64 s[42:43], s[48:49]
	s_mov_b64 s[44:45], s[50:51]
	v_mov_b32_e32 v144, v137
	s_mov_b32 s60, s6
	s_mov_b32 s61, s7
	s_mov_b32 s0, s34
	s_add_i32 s34, s34, 1
	s_mov_b32 s63, -1
	s_mov_b32 s1, 0
	s_mov_b32 s22, 0
	s_mov_b32 s30, 0
	s_cmp_eq_u32 s0, 0
	s_cbranch_scc1 .Lsr_ip2
	s_mov_b32 s63, s0
	s_mov_b32 s30, s100
	s_mov_b32 s22, s100
	s_lshr_b32 s1, s100, 3
	s_mul_i32 s1, s1, s94
